# P3 residual preload issued after the first workgroup barrier of the P2->P3 grid barrier (overlaps the barrier latency), redundant vmcnt(0) at P3 entry skipped when preloaded
# speedup vs baseline: 1.0108x; 1.0083x over previous
; __device__ __forceinline__ void grid_bar(unsigned* ctr, unsigned target) {
;     asm volatile("s_waitcnt vmcnt(0)" ::: "memory");
;     __syncthreads();
;     if (threadIdx.x == 0) {
;         __builtin_amdgcn_fence(__ATOMIC_RELEASE, "agent");
;         asm volatile("s_waitcnt vmcnt(0)" ::: "memory");
;         __hip_atomic_fetch_add(ctr, 1u, __ATOMIC_RELAXED, __HIP_MEMORY_SCOPE_AGENT);
.LBB0_436:
	s_mov_b32 s101, 0
	s_cmp_gt_i32 s79, 3
	v_readlane_b32 s2, v254, 50
	s_cselect_b64 s[0:1], -1, 0
	v_readlane_b32 s3, v254, 51
	s_and_b64 s[2:3], s[2:3], s[0:1]
	s_andn2_b64 vcc, exec, s[2:3]
	s_cbranch_vccnz .LBB0_444
	s_waitcnt vmcnt(0)
	v_cmp_eq_u32_e32 vcc, 0, v229
	s_waitcnt vmcnt(0)
	s_barrier
	s_and_saveexec_b64 s[2:3], vcc
	s_cbranch_execz .LBB0_443
	s_mov_b64 s[4:5], exec
	buffer_wbl2 sc1
	s_waitcnt vmcnt(0)
	v_mbcnt_lo_u32_b32 v0, s4, 0
	v_mbcnt_hi_u32_b32 v0, s5, v0
	v_cmp_eq_u32_e32 vcc, 0, v0
	s_and_saveexec_b64 s[6:7], vcc
	s_cbranch_execz .LBB0_440
	s_bcnt1_i32_b64 s4, s[4:5]
	v_mov_b32_e32 v0, 0
	v_mov_b32_e32 v1, s4
	global_atomic_add v0, v1, s[76:77] offset:256

; #define PG8_STAGE(bufoff, gbase, voff) do { _Pragma("unroll") for (int _i = 0; _i < 2; ++_i) \
;         __builtin_amdgcn_global_load_lds((const unsigned*)((const char*)(gbase) + (voff)[_i]), (PG8_LAS unsigned*)(lds + (bufoff) + ldsw + _i * 8192), 16, 0, 0); } while (0)
; #define PG8_WAIT_V(n) asm volatile("s_waitcnt vmcnt(" #n ")" ::: "memory")
; #define PG8_BAR __builtin_amdgcn_s_barrier()
; template <class Epi, class Sched, bool ALIGN_EPI = false, bool SP2 = false>
; __device__ __forceinline__ void gemm_phase(PG8_LAS unsigned char* lds, const Gemm g, const Sched& S, const Epi& E) {
;     ...
;     const char* cA = (const char*)g.A + (size_t)cur.pm * tstep; const char* cB = (const char*)g.Bt + (size_t)cur.pn * tstep;
;     S.a_ready(cur);
;     if constexpr (SP2) {
;         PG8_STAGE(PG8_SB(0, 0), cB, voffB); PG8_STAGE(PG8_SB(0, 1), cB + hstep, voffB); PG8_STAGE(PG8_SA(0, 0), cA, voffA); PG8_STAGE(PG8_SA(0, 1), cA + hstep, voffA);
;         if (wr == 1) PG8_BAR;
;         PG8_WAIT_V(2); PG8_BAR;
;         PG8_STAGE(PG8_SB(1, 0), cB + kstep, voffB); PG8_STAGE(PG8_SA(1, 0), cA + kstep, voffA); PG8_STAGE(PG8_SB(1, 1), cB + hstep + kstep, voffB);
;         PG8_WAIT_V(6); PG8_BAR;
; __device__ __forceinline__ void grid_bar(unsigned* ctr, unsigned target) {
;     asm volatile("s_waitcnt vmcnt(0)" ::: "memory");
;     __syncthreads();
;     if (threadIdx.x == 0) {
;         __builtin_amdgcn_fence(__ATOMIC_RELEASE, "agent");
;         asm volatile("s_waitcnt vmcnt(0)" ::: "memory");
;         __hip_atomic_fetch_add(ctr, 1u, __ATOMIC_RELAXED, __HIP_MEMORY_SCOPE_AGENT);
;         while (__hip_atomic_load(ctr, __ATOMIC_RELAXED, __HIP_MEMORY_SCOPE_AGENT) < target) __builtin_amdgcn_s_sleep(2);
;         __builtin_amdgcn_fence(__ATOMIC_ACQUIRE, "agent");
;         asm volatile("s_waitcnt vmcnt(0)" ::: "memory");
;     }
;     __syncthreads();
; }
.LBB0_443:
	s_or_b64 exec, exec, s[2:3]
	s_mov_b32 s101, 0
	s_cmpk_gt_i32 s82, 0x1ff
	s_cbranch_scc1 .Lp3_nopre
	s_mov_b32 s101, 1
	v_readlane_b32 s84, v254, 0
	v_readlane_b32 s85, v254, 1
	s_and_b32 s86, s82, 7
	s_lshl_b32 s86, s86, 3
	s_bfe_u32 s87, s82, 0x30003
	s_or_b32 s86, s86, s87
	s_lshr_b32 s87, s82, 6
	v_lshrrev_b32_e32 v250, 8, v229
	v_lshlrev_b32_e32 v250, 6, v250
	v_and_b32_e32 v251, 15, v229
	v_or_b32_e32 v250, v250, v251
	v_lshl_add_u32 v250, s86, 8, v250
	v_bfe_u32 v251, v229, 6, 2
	v_lshlrev_b32_e32 v251, 5, v251
	v_bfe_u32 v252, v229, 4, 2
	v_lshl_or_b32 v251, v252, 2, v251
	v_lshl_add_u32 v251, s87, 8, v251
	v_lshlrev_b32_e32 v250, 13, v250
	v_lshl_add_u32 v250, v251, 2, v250
	global_load_dwordx4 v[124:127], v250, s[84:85]
	global_load_dwordx4 v[120:123], v250, s[84:85] offset:64
	global_load_dwordx4 v[104:107], v250, s[84:85] offset:512
	global_load_dwordx4 v[96:99], v250, s[84:85] offset:576
	s_add_u32 s88, s84, 0x20000
	s_addc_u32 s89, s85, 0
	s_nop 0
	global_load_dwordx4 v[116:119], v250, s[88:89]
	global_load_dwordx4 v[112:115], v250, s[88:89] offset:64
	global_load_dwordx4 v[88:91], v250, s[88:89] offset:512
	global_load_dwordx4 v[84:87], v250, s[88:89] offset:576
	s_add_u32 s90, s84, 0x40000
	s_addc_u32 s91, s85, 0
	s_nop 0
	global_load_dwordx4 v[108:111], v250, s[90:91]
	global_load_dwordx4 v[100:103], v250, s[90:91] offset:64
	global_load_dwordx4 v[76:79], v250, s[90:91] offset:512
	global_load_dwordx4 v[72:75], v250, s[90:91] offset:576
	s_add_u32 s92, s84, 0x60000
	s_addc_u32 s93, s85, 0
	s_nop 0
	global_load_dwordx4 v[92:95], v250, s[92:93]
	global_load_dwordx4 v[80:83], v250, s[92:93] offset:64
	global_load_dwordx4 v[68:71], v250, s[92:93] offset:512
	global_load_dwordx4 v[64:67], v250, s[92:93] offset:576
	s_add_u32 s94, s84, 0x100000
	s_addc_u32 s95, s85, 0
	s_nop 0
	global_load_dwordx4 v[60:63], v250, s[94:95]
	global_load_dwordx4 v[56:59], v250, s[94:95] offset:64
	global_load_dwordx4 v[40:43], v250, s[94:95] offset:512
	global_load_dwordx4 v[32:35], v250, s[94:95] offset:576
	s_add_u32 s96, s84, 0x120000
	s_addc_u32 s97, s85, 0
	s_nop 0
	global_load_dwordx4 v[52:55], v250, s[96:97]
	global_load_dwordx4 v[48:51], v250, s[96:97] offset:64
	global_load_dwordx4 v[24:27], v250, s[96:97] offset:512
	global_load_dwordx4 v[20:23], v250, s[96:97] offset:576
	s_add_u32 s98, s84, 0x140000
	s_addc_u32 s99, s85, 0
	s_nop 0
	global_load_dwordx4 v[44:47], v250, s[98:99]
	global_load_dwordx4 v[36:39], v250, s[98:99] offset:64
	global_load_dwordx4 v[12:15], v250, s[98:99] offset:512
	global_load_dwordx4 v[236:239], v250, s[98:99] offset:576
	s_add_u32 s88, s84, 0x160000
	s_addc_u32 s89, s85, 0
	s_nop 0
	global_load_dwordx4 v[28:31], v250, s[88:89]
	global_load_dwordx4 v[16:19], v250, s[88:89] offset:64
	global_load_dwordx4 v[240:243], v250, s[88:89] offset:512
	global_load_dwordx4 v[244:247], v250, s[88:89] offset:576
.Lp3_nopre:
	s_barrier
.LBB0_444:
	s_cmp_lt_i32 s78, 4
	s_cselect_b64 s[2:3], -1, 0
	s_and_b64 s[0:1], s[2:3], s[0:1]
	s_andn2_b64 vcc, exec, s[0:1]
	s_cbranch_vccnz .LBB0_465
	s_cmpk_gt_i32 s82, 0x1ff
	v_readfirstlane_b32 s1, v229
	s_cbranch_scc1 .LBB0_465
	v_lshlrev_b32_e32 v0, 4, v229
	v_and_b32_e32 v1, 32, v229
	s_cmp_eq_u32 s101, 1
	s_cbranch_scc1 .Lp3_nowait
	s_waitcnt vmcnt(0)
.Lp3_nowait:
	v_bfe_u32 v10, v229, 2, 4
	v_lshrrev_b32_e32 v2, 3, v229
	s_movk_i32 s0, 0x70
	v_add_u32_e32 v11, 0x2000, v0
	v_bitop3_b32 v8, v0, v1, 48 bitop3:0x6c
	v_and_or_b32 v2, v2, s0, v10
	v_lshrrev_b32_e32 v0, 7, v11
	s_movk_i32 s0, 0xf0
	s_ashr_i32 s33, s82, 31
	v_and_or_b32 v0, v0, s0, v10
	s_lshr_b32 s0, s33, 29
	s_add_i32 s0, s82, s0
	s_ashr_i32 s2, s0, 3
	s_and_b32 s0, s0, -8
	s_lshr_b32 s4, s1, 6
	s_sub_i32 s0, s82, s0
	s_lshr_b32 s6, s1, 8
	s_lshl_b32 s30, s4, 10
	s_lshl_b32 s5, s0, 6
	s_mul_i32 s3, s0, 0x41
	s_cmp_lt_i32 s0, 0
	s_cselect_b32 s0, s3, s5
	s_add_i32 s0, s0, s2
	s_ashr_i32 s2, s0, 31
	s_lshr_b32 s2, s2, 26
	s_add_i32 s2, s0, s2
	s_ashr_i32 s3, s2, 6
	s_and_b32 s2, s2, 0xffc0
	s_sub_i32 s2, s0, s2
	s_bfe_i32 s0, s2, 0x80000
	s_bfe_u32 s0, s0, 0x3000c
	s_add_i32 s5, s2, s0
	s_bfe_i32 s0, s5, 0x80000
	s_and_b32 s5, s5, 0xf8
	s_sub_i32 s2, s2, s5
	s_lshl_b32 s3, s3, 3
	s_sext_i32_i16 s0, s0
	s_sext_i32_i8 s2, s2
	s_lshr_b32 s0, s0, 3
	s_add_i32 s24, s3, s2
	s_ashr_i32 s25, s24, 31
	s_bfe_i64 s[8:9], s[0:1], 0x100000
	s_lshl_b64 s[2:3], s[24:25], 20
	s_lshl_b64 s[8:9], s[8:9], 20
	v_and_b32_e32 v9, 64, v229
	s_add_u32 s28, s72, s8
	v_or_b32_e32 v1, v8, v9
	s_addc_u32 s29, s73, s9
	s_add_i32 s25, s30, 0
	v_lshl_or_b32 v128, v2, 12, v1
	s_add_i32 m0, s25, 0x10000
	v_lshl_or_b32 v130, v0, 12, v1
	global_load_lds_dwordx4 v128, s[28:29]
	s_add_i32 m0, s25, 0x12000
	s_add_u32 s8, s28, 0x80000
	global_load_lds_dwordx4 v130, s[28:29]
	s_addc_u32 s9, s29, 0
	s_add_i32 m0, s25, 0x14000
	v_mov_b32_e32 v129, 0
	global_load_lds_dwordx4 v128, s[8:9]
	s_add_i32 m0, s25, 0x16000
	s_add_u32 s26, s80, s2
	s_addc_u32 s27, s81, s3
	s_add_i32 s36, s25, 0x2000
	global_load_lds_dwordx4 v130, s[8:9]
	s_mov_b32 m0, s25
	s_add_u32 s2, s26, 0x80000
	global_load_lds_dwordx4 v128, s[26:27]
	s_mov_b32 m0, s36
	s_addc_u32 s3, s27, 0
	s_add_i32 s37, s25, 0x4000
	global_load_lds_dwordx4 v130, s[26:27]
	s_mov_b32 m0, s37
	s_add_i32 s38, s25, 0x6000
	global_load_lds_dwordx4 v128, s[2:3]
	s_mov_b32 m0, s38
	v_mov_b32_e32 v131, v129
	global_load_lds_dwordx4 v130, s[2:3]
	s_cmp_eq_u32 s6, 1
	s_mov_b32 s39, 0
	v_lshl_add_u64 v[6:7], s[28:29], 0, v[128:129]
	v_lshl_add_u64 v[4:5], s[28:29], 0, v[130:131]
	v_lshl_add_u64 v[0:1], s[26:27], 0, v[128:129]
	s_cselect_b64 s[2:3], -1, 0
	s_cmp_lg_u32 s6, 1
	v_lshl_add_u64 v[2:3], s[26:27], 0, v[130:131]
	s_cbranch_scc1 .LBB0_448
	s_barrier
